# MLA attention: Q-fragment vmcnt ladder hoisted out of the tile loop (it was draining the next tile's K/V prefetch); P8 w_down copy on idle workgroups
# speedup vs baseline: 1.0392x; 1.0064x over previous
; template <int NKS, bool ALLIN = false> ...
;     ...
;     int tid_ = tid_in; asm volatile("" : "+v"(tid_)); const int tid = tid_, lane = tid & 63, wid = __builtin_amdgcn_readfirstlane(tid >> 6), r = lane & 31, hh = lane >> 5;
;     bf16x8 qf[NKS];
; #pragma unroll
;     for (int ks = 0; ks < NKS; ++ks) {
;         if (ks < 8) qf[ks] = *(const bf16x8*)(qn + (size_t)(wid * 32 + r) * ldqn + ks * 16 + hh * 8);
;         else qf[ks] = *(const bf16x8*)(qpe + (size_t)(wid * 32 + r) * ldqpe + (ks - 8) * 16 + hh * 8);
;     }
;     const int key0 = tid >> 4, ch0 = tid & 15;
;     const int keyp = tid >> 3, chp = tid & 7;
;     u32x4 rk0, rk1, rkp, rv0, rv1;
;     ...
;     if constexpr (ALLIN) {
;         u32x4 ak0[4], ak1[4], av0[4], av1[4];
; #pragma unroll
;         for (int t = 0; t < 4; ++t) { ATT_LOAD(t); ak0[t] = rk0; ak1[t] = rk1; av0[t] = rv0; av1[t] = rv1; }
; #pragma unroll
;         for (int t = 0; t < 4; ++t) { rk0 = ak0[t]; rk1 = ak1[t]; rv0 = av0[t]; rv1 = av1[t]; ATT_STORE(t); }
;     } else { ATT_LOAD(0); ATT_STORE(0); }
;     __syncthreads();
;     f32x16 o[4];
; #pragma unroll
;     for (int d = 0; d < 4; ++d)
; #pragma unroll
;         for (int i = 0; i < 16; ++i) o[d][i] = 0.f;
;     float mrun = -INFINITY, lrun = 0.f;
;     const int g4 = lane >> 4, i16 = lane & 15, q4 = i16 >> 2, p4 = i16 & 3;
;     const int vlane = (4 * hh + q4) * VSTR + (16 * (g4 & 1) + 4 * p4) * 2;
.LBB0_100:
	s_lshl_b32 s14, s30, 3
	s_ashr_i32 s15, s30, 7
	s_and_b32 s14, s14, 56
	s_and_b32 s35, s15, -2
	s_add_i32 s14, s14, s35
	s_bfe_u32 s34, s30, 0x10007
	s_ashr_i32 s18, s14, 4
	s_and_b32 s14, s14, 14
	s_bfe_u32 s15, s30, 0x40003
	s_and_b32 s33, s29, 8
	s_or_b32 s20, s14, s34
	s_and_b32 s14, s30, 0x100
	s_xor_b32 s16, s15, 15
	s_cmp_eq_u32 s14, 0
	s_cselect_b32 s36, s15, s16
	s_ashr_i32 s19, s18, 31
	s_lshl_b32 s14, s36, 19
	s_lshl_b64 s[16:17], s[18:19], 23
	s_or_b32 s16, s16, s14
	s_lshl_b64 s[14:15], s[16:17], 1
	s_add_u32 s21, s64, s14
	s_addc_u32 s22, s65, s15
	s_lshl_b32 s31, s20, 7
	s_lshl_b32 s37, s20, 8
	s_add_u32 s20, s21, s37
	s_addc_u32 s21, s22, 0
	s_add_u32 s16, s8, s16
	s_addc_u32 s17, s9, s17
	s_add_u32 s22, s16, s31
	s_addc_u32 s23, s17, 0
	s_lshl_b64 s[16:17], s[18:19], 24
	v_readlane_b32 s40, v254, 7
	v_readlane_b32 s41, v254, 8
	s_add_u32 s38, s40, s16
	s_addc_u32 s41, s41, s17
	s_add_u32 s40, s38, s37
	v_mov_b32_e32 v14, v210
	s_addc_u32 s41, s41, 0
	s_lshl_b64 s[18:19], s[18:19], 19
	s_add_u32 s42, s26, s18
	v_ashrrev_i32_e32 v2, 4, v14
	v_ashrrev_i32_e32 v3, 31, v2
	s_addc_u32 s43, s27, s19
	v_lshlrev_b64 v[6:7], 12, v[2:3]
	v_lshlrev_b32_e32 v0, 4, v14
	s_add_u32 s38, s24, s16
	v_lshl_add_u64 v[8:9], s[40:41], 0, v[6:7]
	v_and_b32_e32 v202, 0xf0, v0
	v_mov_b32_e32 v203, v1
	s_addc_u32 s45, s25, s17
	v_ashrrev_i32_e32 v4, 3, v14
	v_lshl_add_u64 v[8:9], v[8:9], 0, v[202:203]
	s_add_u32 s44, s38, s37
	v_add_co_u32_e32 v10, vcc, s71, v8
	v_ashrrev_i32_e32 v5, 31, v4
	s_addc_u32 s45, s45, 0
	v_addc_co_u32_e32 v11, vcc, 0, v9, vcc
	global_load_dwordx4 v[112:115], v[8:9], off
	global_load_dwordx4 v[116:119], v[10:11], off
	v_lshlrev_b64 v[8:9], 7, v[4:5]
	v_lshl_add_u64 v[10:11], s[42:43], 0, v[8:9]
	v_and_b32_e32 v204, 0x70, v0
	v_mov_b32_e32 v205, v1
	v_lshl_add_u64 v[12:13], s[44:45], 0, v[6:7]
	v_lshl_add_u64 v[10:11], v[10:11], 0, v[204:205]
	v_lshl_add_u64 v[12:13], v[12:13], 0, v[202:203]
	v_readfirstlane_b32 s37, v14
	global_load_dwordx4 v[120:123], v[10:11], off
	global_load_dwordx4 v[124:127], v[12:13], off
	v_add_co_u32_e32 v10, vcc, s71, v12
	s_ashr_i32 s37, s37, 1
	s_nop 0
	v_addc_co_u32_e32 v11, vcc, 0, v13, vcc
	v_mov_b32_e32 v5, s37
	global_load_dwordx4 v[128:131], v[10:11], off
	v_bfi_b32 v10, s70, v5, v14
	v_ashrrev_i32_e32 v11, 31, v10
	v_bfe_u32 v3, v14, 5, 1
	v_lshlrev_b64 v[12:13], 11, v[10:11]
	v_lshlrev_b64 v[200:201], 12, v[10:11]
	v_lshlrev_b32_e32 v0, 4, v3
	v_lshl_add_u64 v[10:11], s[22:23], 0, v[12:13]
	v_lshl_add_u64 v[12:13], s[20:21], 0, v[200:201]
	v_lshl_add_u64 v[12:13], v[12:13], 0, v[0:1]
	v_lshl_add_u64 v[10:11], v[10:11], 0, v[0:1]
	global_load_dwordx4 v[132:135], v[12:13], off
	global_load_dwordx4 v[136:139], v[12:13], off offset:32
	global_load_dwordx4 v[140:143], v[12:13], off offset:64
	global_load_dwordx4 v[144:147], v[12:13], off offset:96
	global_load_dwordx4 v[148:151], v[12:13], off offset:128
	global_load_dwordx4 v[152:155], v[12:13], off offset:160
	global_load_dwordx4 v[156:159], v[12:13], off offset:192
	global_load_dwordx4 v[160:163], v[12:13], off offset:224
	global_load_dwordx4 v[164:167], v[10:11], off
	global_load_dwordx4 v[168:171], v[10:11], off offset:32
	global_load_dwordx4 v[172:175], v[10:11], off offset:64
	global_load_dwordx4 v[176:179], v[10:11], off offset:96
	v_mul_lo_u32 v205, v2, s81
	s_movk_i32 s20, 0xffb0
	v_mul_lo_u32 v211, v4, s81
	v_mul_lo_u32 v212, v2, s75
	v_mul_lo_u32 v2, v2, s20
	v_add3_u32 v4, 0, v205, v202
	s_lshl_b32 s21, s36, 2
	s_movk_i32 s23, 0x3200
	v_add_u32_e32 v11, v4, v2
	s_add_i32 s20, s21, 4
	s_add_i32 s21, s21, s28
	v_add3_u32 v2, v4, s23, v2
	v_add3_u32 v10, 0, v211, v204
	v_lshlrev_b32_e32 v203, 2, v3
	v_and_b32_e32 v3, 16, v14
	s_add_u32 s18, s18, 0x402000
	s_addc_u32 s19, s19, 0
	s_add_i32 s33, s33, s35
	v_and_b32_e32 v5, 31, v14
	v_lshl_add_u64 v[208:209], s[16:17], 0, v[6:7]
	s_lshl_b32 s16, s33, 8
	s_waitcnt vmcnt(16)
	ds_write_b128 v4, v[112:115]
	s_waitcnt vmcnt(15)
	ds_write_b128 v4, v[116:119] offset:12800
	s_waitcnt vmcnt(14)
	ds_write_b128 v10, v[120:123] offset:256
	s_waitcnt vmcnt(13)
	ds_write_b128 v11, v[124:127] offset:51200
	v_lshlrev_b32_e32 v4, 2, v14
	v_and_or_b32 v3, v4, 12, v3
	v_lshlrev_b32_e32 v3, 1, v3
	s_and_b32 s16, s16, 0xe00
	s_lshl_b32 s17, s34, 8
	v_mov_b32_e32 v15, v1
	s_waitcnt vmcnt(12)
	ds_write_b128 v2, v[128:131] offset:48640
	v_lshrrev_b32_e32 v2, 2, v14
	v_and_or_b32 v2, v2, 3, v203
	v_mul_u32_u24_e32 v2, 0x140, v2
	v_add3_u32 v213, 0, v2, v3
	v_mul_u32_u24_e32 v2, 0x190, v5
	v_mov_b32_e32 v14, v1
	v_add3_u32 v215, 0, v2, v0
	v_lshl_add_u64 v[206:207], s[18:19], 0, v[8:9]
	v_readlane_b32 s34, v254, 34
	s_or_b32 s16, s16, s17
	v_mov_b32_e32 v0, v1
	v_mov_b32_e32 v2, v1
	v_mov_b32_e32 v3, v1
	v_mov_b32_e32 v4, v1
	v_mov_b32_e32 v5, v1
	v_mov_b32_e32 v6, v1
	v_mov_b32_e32 v7, v1
	v_mov_b32_e32 v8, v1
	v_mov_b32_e32 v9, v1
	v_mov_b32_e32 v10, v1
	v_mov_b32_e32 v11, v1
	v_mov_b32_e32 v12, v1
	v_mov_b32_e32 v13, v1
	v_mov_b64_e32 v[30:31], v[14:15]
	v_mov_b64_e32 v[46:47], v[14:15]
	v_mov_b64_e32 v[62:63], v[14:15]
	v_mov_b64_e32 v[78:79], v[14:15]
	s_mov_b32 s22, 0
	v_or_b32_e32 v206, v206, v204
	v_readlane_b32 s35, v254, 35
	v_or3_b32 v208, v208, v202, s16
	v_add_u32_e32 v216, 0x3200, v205
	v_add_u32_e32 v217, 0x2800, v212
	v_mov_b32_e32 v219, 0xff800000
	v_mov_b32_e32 v214, 0
	v_mov_b64_e32 v[28:29], v[12:13]
	v_mov_b64_e32 v[26:27], v[10:11]
	v_mov_b64_e32 v[24:25], v[8:9]
	v_mov_b64_e32 v[22:23], v[6:7]
	v_mov_b64_e32 v[20:21], v[4:5]
	v_mov_b64_e32 v[18:19], v[2:3]
	v_mov_b64_e32 v[16:17], v[0:1]
	v_mov_b64_e32 v[44:45], v[12:13]
	v_mov_b64_e32 v[42:43], v[10:11]
	v_mov_b64_e32 v[40:41], v[8:9]
	v_mov_b64_e32 v[38:39], v[6:7]
	v_mov_b64_e32 v[36:37], v[4:5]
	v_mov_b64_e32 v[34:35], v[2:3]
	v_mov_b64_e32 v[32:33], v[0:1]
	v_mov_b64_e32 v[60:61], v[12:13]
	v_mov_b64_e32 v[58:59], v[10:11]
	v_mov_b64_e32 v[56:57], v[8:9]
	v_mov_b64_e32 v[54:55], v[6:7]
	v_mov_b64_e32 v[52:53], v[4:5]
	v_mov_b64_e32 v[50:51], v[2:3]
	v_mov_b64_e32 v[48:49], v[0:1]
	v_mov_b64_e32 v[76:77], v[12:13]
	v_mov_b64_e32 v[74:75], v[10:11]
	v_mov_b64_e32 v[72:73], v[8:9]
	v_mov_b64_e32 v[70:71], v[6:7]
	v_mov_b64_e32 v[68:69], v[4:5]
	v_mov_b64_e32 v[66:67], v[2:3]
	v_mov_b64_e32 v[64:65], v[0:1]
	s_waitcnt vmcnt(0)
	s_waitcnt lgkmcnt(0)
	s_barrier

; #define LAS __attribute__((address_space(3)))
; #define MFMA32(a, b, c) __builtin_amdgcn_mfma_f32_32x32x16_bf16((a), (b), (c), 0, 0, 0)
; #define ATT_LDK(buf, g) do { _Pragma("unroll") for (int kk = 0; kk < 2; ++kk) { \
;                 ka[buf][kk][0] = *(const LAS bf16x8*)(Kb + r * KSTR + (2 * (g) + kk) * 32 + hh * 16); ka[buf][kk][1] = *(const LAS bf16x8*)(Kb + (32 + r) * KSTR + (2 * (g) + kk) * 32 + hh * 16); } } while (0)
; #define ATT_LDV(buf, d) do { _Pragma("unroll") for (int kb = 0; kb < 2; ++kb) _Pragma("unroll") for (int s = 0; s < 2; ++s) { \
;                 const LAS unsigned char* p_ = Vb + vlane + (32 * kb + 16 * s) * VSTR + (d) * 64; vl[buf][2 * kb + s] = trread(p_); vh[buf][2 * kb + s] = trread(p_ + 8 * VSTR); } } while (0)
; template <int NKS, bool ALLIN = false> ...
;     ...
;             const int bi_ = ALLIN ? t : (t & 1);
;             const LAS unsigned char* Kb = lds + bi_ * KBUF; const LAS unsigned char* Vb = lds + NKB * KBUF + bi_ * VBUF;
;             f32x16 s0, s1;
; #pragma unroll
;             for (int i = 0; i < 16; ++i) { s0[i] = 0.f; s1[i] = 0.f; }
;             bf16x8 ka[2][2][2];
;     ...
;             ATT_LDK(0, 0); ATT_LDK(1, 1);
;             __builtin_amdgcn_sched_barrier(0);
; #pragma unroll
;             for (int g = 0; g < NKS / 2; ++g) {
; #pragma unroll
;                 for (int kk = 0; kk < 2; ++kk) { s0 = MFMA32(ka[g & 1][kk][0], qf[2 * g + kk], s0); s1 = MFMA32(ka[g & 1][kk][1], qf[2 * g + kk], s1); }
;                 __builtin_amdgcn_sched_barrier(0);
;                 if (g + 2 < NKS / 2) { ATT_LDK(g & 1, g + 2); __builtin_amdgcn_sched_barrier(0); }
;             }
;     ...
;             s16x4 vl[2][4], vh[2][4];
;     ...
;             ATT_LDV(0, 0); ATT_LDV(1, 1);
;             __builtin_amdgcn_sched_barrier(0);
;             float mx = -INFINITY;
; #pragma unroll
;             for (int i = 0; i < 16; ++i) mx = fmaxf(mx, fmaxf(s0[i], s1[i]));
;             mx = fmaxf(mx, __shfl_xor(mx, 32)) * c2;
.LBB0_108:
	s_and_b32 s19, s22, 1
	s_mul_i32 s22, s19, 0x6400
	v_add_u32_e32 v0, s22, v215
	ds_read_b128 v[2:5], v0
	ds_read_b128 v[6:9], v0 offset:32
	ds_read_b128 v[10:13], v0 offset:12800
	ds_read_b128 v[180:183], v0 offset:12832
	ds_read_b128 v[184:187], v0 offset:64
	ds_read_b128 v[188:191], v0 offset:96
	ds_read_b128 v[192:195], v0 offset:12864
	ds_read_b128 v[196:199], v0 offset:12896
	s_mulk_i32 s19, 0x5000
	s_waitcnt lgkmcnt(7)
	v_mfma_f32_32x32x16_bf16 v[96:111], v[2:5], v[132:135], 0
	s_waitcnt lgkmcnt(5)
	v_mfma_f32_32x32x16_bf16 v[80:95], v[10:13], v[132:135], 0
	v_mfma_f32_32x32x16_bf16 v[96:111], v[6:9], v[136:139], v[96:111]
	s_waitcnt lgkmcnt(4)
	v_mfma_f32_32x32x16_bf16 v[80:95], v[180:183], v[136:139], v[80:95]
	ds_read_b128 v[2:5], v0 offset:128
	ds_read_b128 v[6:9], v0 offset:160
	ds_read_b128 v[10:13], v0 offset:12928
	ds_read_b128 v[180:183], v0 offset:12960
	s_waitcnt lgkmcnt(7)
	v_mfma_f32_32x32x16_bf16 v[96:111], v[184:187], v[140:143], v[96:111]
	s_waitcnt lgkmcnt(5)
	v_mfma_f32_32x32x16_bf16 v[80:95], v[192:195], v[140:143], v[80:95]
	v_mfma_f32_32x32x16_bf16 v[96:111], v[188:191], v[144:147], v[96:111]
	s_waitcnt lgkmcnt(4)
	v_mfma_f32_32x32x16_bf16 v[80:95], v[196:199], v[144:147], v[80:95]
	ds_read_b128 v[184:187], v0 offset:192
	ds_read_b128 v[188:191], v0 offset:224
	ds_read_b128 v[192:195], v0 offset:12992
	ds_read_b128 v[196:199], v0 offset:13024
	s_waitcnt lgkmcnt(7)
	v_mfma_f32_32x32x16_bf16 v[96:111], v[2:5], v[148:151], v[96:111]
	s_waitcnt lgkmcnt(5)
	v_mfma_f32_32x32x16_bf16 v[80:95], v[10:13], v[148:151], v[80:95]
	v_mfma_f32_32x32x16_bf16 v[96:111], v[6:9], v[152:155], v[96:111]
	s_waitcnt lgkmcnt(4)
	v_mfma_f32_32x32x16_bf16 v[80:95], v[180:183], v[152:155], v[80:95]
	ds_read_b128 v[2:5], v0 offset:256
	ds_read_b128 v[6:9], v0 offset:288
	ds_read_b128 v[10:13], v0 offset:13056
	ds_read_b128 v[180:183], v0 offset:13088
	s_waitcnt lgkmcnt(7)
	v_mfma_f32_32x32x16_bf16 v[96:111], v[184:187], v[156:159], v[96:111]
	s_waitcnt lgkmcnt(5)
	v_mfma_f32_32x32x16_bf16 v[80:95], v[192:195], v[156:159], v[80:95]
	v_mfma_f32_32x32x16_bf16 v[96:111], v[188:191], v[160:163], v[96:111]
	s_waitcnt lgkmcnt(4)
	v_mfma_f32_32x32x16_bf16 v[80:95], v[196:199], v[160:163], v[80:95]
	ds_read_b128 v[184:187], v0 offset:320
	ds_read_b128 v[188:191], v0 offset:352
	ds_read_b128 v[192:195], v0 offset:13120
	ds_read_b128 v[196:199], v0 offset:13152
	s_waitcnt lgkmcnt(7)
	v_mfma_f32_32x32x16_bf16 v[96:111], v[2:5], v[164:167], v[96:111]
	s_waitcnt lgkmcnt(5)
	v_mfma_f32_32x32x16_bf16 v[80:95], v[10:13], v[164:167], v[80:95]
	v_mfma_f32_32x32x16_bf16 v[96:111], v[6:9], v[168:171], v[96:111]
	s_waitcnt lgkmcnt(4)
	v_mfma_f32_32x32x16_bf16 v[80:95], v[180:183], v[168:171], v[80:95]
	s_waitcnt lgkmcnt(3)
	v_mfma_f32_32x32x16_bf16 v[96:111], v[184:187], v[172:175], v[96:111]
	s_waitcnt lgkmcnt(1)
	v_mfma_f32_32x32x16_bf16 v[80:95], v[192:195], v[172:175], v[80:95]
	v_mfma_f32_32x32x16_bf16 v[96:111], v[188:191], v[176:179], v[96:111]
	s_waitcnt lgkmcnt(0)
	v_mfma_f32_32x32x16_bf16 v[80:95], v[196:199], v[176:179], v[80:95]
	v_add_u32_e32 v222, s19, v213
	v_add_u32_e32 v218, 0xc800, v222
	ds_read_b64_tr_b16 v[184:185], v222 offset:51200
	ds_read_b64_tr_b16 v[186:187], v222 offset:53760
	ds_read_b64_tr_b16 v[182:183], v222 offset:53824
	ds_read_b64_tr_b16 v[180:181], v222 offset:51264
	ds_read_b64_tr_b16 v[196:197], v222 offset:56320
	ds_read_b64_tr_b16 v[198:199], v222 offset:58880
	ds_read_b64_tr_b16 v[12:13], v222 offset:58944
	ds_read_b64_tr_b16 v[10:11], v222 offset:56384
	ds_read_b64_tr_b16 v[192:193], v222 offset:61440
	ds_read_b64_tr_b16 v[194:195], v222 offset:64000
	ds_read_b64_tr_b16 v[8:9], v222 offset:64064
	ds_read_b64_tr_b16 v[6:7], v222 offset:61504
	ds_read_b64_tr_b16 v[188:189], v218 offset:15360
	ds_read_b64_tr_b16 v[190:191], v218 offset:17920
	ds_read_b64_tr_b16 v[4:5], v218 offset:17984
	ds_read_b64_tr_b16 v[2:3], v218 offset:15424
	v_max_f32_e32 v0, v80, v80
	v_max_f32_e32 v14, v96, v96
	v_max_f32_e32 v0, v14, v0
	v_max_f32_e32 v14, v81, v81
	v_max_f32_e32 v15, v97, v97
	v_max_f32_e32 v14, v15, v14
	v_max3_f32 v0, v0, s73, v14
	v_max_f32_e32 v14, v82, v82
	v_max_f32_e32 v15, v98, v98
	v_max_f32_e32 v14, v15, v14
	v_max_f32_e32 v15, v83, v83
	v_max_f32_e32 v223, v99, v99
	v_max_f32_e32 v15, v223, v15
	v_max3_f32 v0, v0, v14, v15
	v_max_f32_e32 v14, v84, v84
	v_max_f32_e32 v15, v100, v100
	v_max_f32_e32 v14, v15, v14
	v_max_f32_e32 v15, v85, v85
	v_max_f32_e32 v223, v101, v101
	v_max_f32_e32 v15, v223, v15
	v_max3_f32 v0, v0, v14, v15
	v_max_f32_e32 v14, v86, v86
	v_max_f32_e32 v15, v102, v102
	v_max_f32_e32 v14, v15, v14
	v_max_f32_e32 v15, v87, v87
	v_max_f32_e32 v223, v103, v103
	v_max_f32_e32 v15, v223, v15
	v_max3_f32 v0, v0, v14, v15
	v_max_f32_e32 v14, v88, v88
	v_max_f32_e32 v15, v104, v104
	v_max_f32_e32 v14, v15, v14
	v_max_f32_e32 v15, v89, v89
	v_max_f32_e32 v223, v105, v105
	v_max_f32_e32 v15, v223, v15
	v_max3_f32 v0, v0, v14, v15
	v_max_f32_e32 v14, v90, v90
	v_max_f32_e32 v15, v106, v106
	v_max_f32_e32 v14, v15, v14
	v_max_f32_e32 v15, v91, v91
	v_max_f32_e32 v223, v107, v107
	v_max_f32_e32 v15, v223, v15
	v_max3_f32 v0, v0, v14, v15
	v_max_f32_e32 v14, v92, v92
	v_max_f32_e32 v15, v108, v108
	v_max_f32_e32 v14, v15, v14
	v_max_f32_e32 v15, v93, v93
	v_max_f32_e32 v223, v109, v109
	v_max_f32_e32 v15, v223, v15
	v_max3_f32 v0, v0, v14, v15
	v_max_f32_e32 v14, v94, v94
	v_max_f32_e32 v15, v110, v110
	v_max_f32_e32 v14, v15, v14
	v_max_f32_e32 v15, v95, v95
	v_max_f32_e32 v223, v111, v111
	v_max_f32_e32 v15, v223, v15
	v_max3_f32 v0, v0, v14, v15
	v_and_b32_e32 v15, 64, v220
	v_xor_b32_e32 v14, 32, v220
	v_add_u32_e32 v15, 64, v15
	v_cmp_lt_i32_e32 vcc, v14, v15
	s_nop 1
	v_cndmask_b32_e32 v14, v220, v14, vcc
	v_lshlrev_b32_e32 v14, 2, v14
	ds_bpermute_b32 v14, v14, v0
	s_waitcnt lgkmcnt(0)
; #define MFMA32(a, b, c) __builtin_amdgcn_mfma_f32_32x32x16_bf16((a), (b), (c), 0, 0, 0)
; __device__ __forceinline__ bf16x8 cat44(s16x4 lo, s16x4 hi) { return (bf16x8){lo[0], lo[1], lo[2], lo[3], hi[0], hi[1], hi[2], hi[3]}; }
; #define ATT_LDV(buf, d) do { _Pragma("unroll") for (int kb = 0; kb < 2; ++kb) _Pragma("unroll") for (int s = 0; s < 2; ++s) { \
;                 const LAS unsigned char* p_ = Vb + vlane + (32 * kb + 16 * s) * VSTR + (d) * 64; vl[buf][2 * kb + s] = trread(p_); vh[buf][2 * kb + s] = trread(p_ + 8 * VSTR); } } while (0)
; template <int NKS, bool ALLIN = false> ...
;     ...
;             mx = fmaxf(mx, __shfl_xor(mx, 32)) * c2;
;             const float mnew = fmaxf(mrun, mx), alpha = __builtin_amdgcn_exp2f(mrun - mnew); mrun = mnew;
;             float ls = 0.f;
; #pragma unroll
;             for (int i = 0; i < 16; ++i) { s0[i] = __builtin_amdgcn_exp2f(fmaf(s0[i], c2, -mnew)); s1[i] = __builtin_amdgcn_exp2f(fmaf(s1[i], c2, -mnew)); ls += s0[i] + s1[i]; }
;             lrun = lrun * alpha + ls;
; #pragma unroll
;             for (int d = 0; d < 4; ++d)
; #pragma unroll
;                 for (int i = 0; i < 16; ++i) o[d][i] *= alpha;
;             bf16x8 pf[4];
;             pf[0] = packacc8(s0, 0); pf[1] = packacc8(s0, 8); pf[2] = packacc8(s1, 0); pf[3] = packacc8(s1, 8);
;             __builtin_amdgcn_sched_barrier(0);
; #pragma unroll
;             for (int d = 0; d < 4; ++d) {
; #pragma unroll
;                 for (int j = 0; j < 4; ++j) o[d] = MFMA32(cat44(vl[d & 1][j], vh[d & 1][j]), pf[j], o[d]);
;                 __builtin_amdgcn_sched_barrier(0);
;                 if (d + 2 < 4) { ATT_LDV(d & 1, d + 2); __builtin_amdgcn_sched_barrier(0); }
;             }
	v_max_f32_e32 v14, v14, v14
	v_max_f32_e32 v0, v0, v14
	v_mul_f32_e32 v0, 0x3dd53b94, v0
	v_max_f32_e32 v14, v219, v219
	v_max_f32_e32 v223, v14, v0
	v_fma_f32 v14, v98, s80, -v223
	v_exp_f32_e32 v234, v14
	v_fma_f32 v14, v82, s80, -v223
	v_fma_f32 v0, v96, s80, -v223
	v_exp_f32_e32 v235, v14
	v_fma_f32 v14, v99, s80, -v223
	v_exp_f32_e32 v224, v0
	v_fma_f32 v0, v80, s80, -v223
	v_exp_f32_e32 v236, v14
	v_fma_f32 v14, v83, s80, -v223
	v_exp_f32_e32 v225, v0
	v_fma_f32 v0, v97, s80, -v223
	v_exp_f32_e32 v237, v14
	v_fma_f32 v14, v100, s80, -v223
	v_exp_f32_e32 v226, v0
	v_fma_f32 v0, v81, s80, -v223
	v_exp_f32_e32 v81, v14
	v_fma_f32 v14, v84, s80, -v223
	v_exp_f32_e32 v15, v14
	v_fma_f32 v14, v101, s80, -v223
	v_fma_f32 v82, v102, s80, -v223
	v_exp_f32_e32 v80, v14
	v_fma_f32 v14, v85, s80, -v223
	v_exp_f32_e32 v85, v82
	v_fma_f32 v82, v86, s80, -v223
	v_fma_f32 v86, v104, s80, -v223
	v_exp_f32_e32 v101, v86
	v_fma_f32 v86, v88, s80, -v223
	v_fma_f32 v88, v106, s80, -v223
	v_exp_f32_e32 v83, v82
	v_fma_f32 v82, v103, s80, -v223
	v_exp_f32_e32 v103, v88
	v_fma_f32 v88, v90, s80, -v223
	v_exp_f32_e32 v84, v82
	v_fma_f32 v82, v87, s80, -v223
	v_exp_f32_e32 v87, v86
	v_fma_f32 v86, v105, s80, -v223
	v_exp_f32_e32 v105, v88
	v_fma_f32 v88, v107, s80, -v223
	v_exp_f32_e32 v102, v88
	v_fma_f32 v88, v91, s80, -v223
	v_exp_f32_e32 v227, v0
	v_exp_f32_e32 v104, v88
	v_fma_f32 v88, v108, s80, -v223
	v_exp_f32_e32 v107, v88
	v_fma_f32 v88, v92, s80, -v223
	v_exp_f32_e32 v231, v88
	v_fma_f32 v88, v109, s80, -v223
	v_sub_f32_e32 v0, v219, v223
	v_add_f32_e32 v219, v224, v225
	v_exp_f32_e32 v14, v14
	v_exp_f32_e32 v106, v88
	v_fma_f32 v88, v93, s80, -v223
	v_add_f32_e32 v229, v226, v227
	v_exp_f32_e32 v230, v88
	v_fma_f32 v88, v110, s80, -v223
	v_add_f32_e32 v110, 0, v219
	v_exp_f32_e32 v82, v82
	v_add_f32_e32 v238, v234, v235
	v_add_f32_e32 v110, v229, v110
	v_add_f32_e32 v239, v236, v237
	v_exp_f32_e32 v100, v86
	v_fma_f32 v86, v89, s80, -v223
	v_add_f32_e32 v110, v238, v110
	v_pk_add_f32 v[96:97], v[80:81], v[14:15]
	v_exp_f32_e32 v86, v86
	v_add_f32_e32 v110, v239, v110
	v_exp_f32_e32 v109, v88
	v_fma_f32 v88, v94, s80, -v223
	v_add_f32_e32 v97, v97, v110
	v_pk_add_f32 v[98:99], v[84:85], v[82:83]
	v_exp_f32_e32 v233, v88
	v_fma_f32 v88, v111, s80, -v223
	v_add_f32_e32 v96, v96, v97
	v_exp_f32_e32 v108, v88
	v_fma_f32 v88, v95, s80, -v223
	v_add_f32_e32 v96, v99, v96
	v_exp_f32_e32 v232, v88
	v_pk_add_f32 v[88:89], v[100:101], v[86:87]
	v_add_f32_e32 v96, v98, v96
	v_add_f32_e32 v89, v89, v96
	v_pk_add_f32 v[90:91], v[102:103], v[104:105]
	v_add_f32_e32 v88, v88, v89
	v_add_f32_e32 v88, v91, v88
	v_exp_f32_e32 v0, v0
	v_pk_add_f32 v[92:93], v[106:107], v[230:231]
	v_add_f32_e32 v88, v90, v88
	v_add_f32_e32 v88, v93, v88
	v_pk_add_f32 v[94:95], v[108:109], v[232:233]
	v_add_f32_e32 v88, v92, v88
	v_add_f32_e32 v88, v95, v88
	v_pk_mul_f32 v[78:79], v[78:79], v[0:1] op_sel_hi:[1,0]
	v_pk_mul_f32 v[76:77], v[76:77], v[0:1] op_sel_hi:[1,0]
	v_pk_mul_f32 v[74:75], v[74:75], v[0:1] op_sel_hi:[1,0]
	v_pk_mul_f32 v[72:73], v[72:73], v[0:1] op_sel_hi:[1,0]
	v_pk_mul_f32 v[70:71], v[70:71], v[0:1] op_sel_hi:[1,0]
	v_pk_mul_f32 v[68:69], v[68:69], v[0:1] op_sel_hi:[1,0]
	v_pk_mul_f32 v[66:67], v[66:67], v[0:1] op_sel_hi:[1,0]
	v_pk_mul_f32 v[64:65], v[64:65], v[0:1] op_sel_hi:[1,0]
	v_pk_mul_f32 v[62:63], v[62:63], v[0:1] op_sel_hi:[1,0]
	v_pk_mul_f32 v[60:61], v[60:61], v[0:1] op_sel_hi:[1,0]
	v_pk_mul_f32 v[58:59], v[58:59], v[0:1] op_sel_hi:[1,0]
	v_pk_mul_f32 v[56:57], v[56:57], v[0:1] op_sel_hi:[1,0]
	v_pk_mul_f32 v[54:55], v[54:55], v[0:1] op_sel_hi:[1,0]
	v_pk_mul_f32 v[52:53], v[52:53], v[0:1] op_sel_hi:[1,0]
	v_pk_mul_f32 v[50:51], v[50:51], v[0:1] op_sel_hi:[1,0]
	v_pk_mul_f32 v[48:49], v[48:49], v[0:1] op_sel_hi:[1,0]
	v_pk_mul_f32 v[46:47], v[46:47], v[0:1] op_sel_hi:[1,0]
	v_pk_mul_f32 v[44:45], v[44:45], v[0:1] op_sel_hi:[1,0]
	v_pk_mul_f32 v[42:43], v[42:43], v[0:1] op_sel_hi:[1,0]
	v_pk_mul_f32 v[40:41], v[40:41], v[0:1] op_sel_hi:[1,0]
	v_pk_mul_f32 v[38:39], v[38:39], v[0:1] op_sel_hi:[1,0]
	v_pk_mul_f32 v[36:37], v[36:37], v[0:1] op_sel_hi:[1,0]
	v_pk_mul_f32 v[34:35], v[34:35], v[0:1] op_sel_hi:[1,0]
	v_pk_mul_f32 v[32:33], v[32:33], v[0:1] op_sel_hi:[1,0]
	v_pk_mul_f32 v[30:31], v[30:31], v[0:1] op_sel_hi:[1,0]
	v_pk_mul_f32 v[28:29], v[28:29], v[0:1] op_sel_hi:[1,0]
	v_pk_mul_f32 v[26:27], v[26:27], v[0:1] op_sel_hi:[1,0]
	v_pk_mul_f32 v[24:25], v[24:25], v[0:1] op_sel_hi:[1,0]
	v_pk_mul_f32 v[22:23], v[22:23], v[0:1] op_sel_hi:[1,0]
	v_pk_mul_f32 v[20:21], v[20:21], v[0:1] op_sel_hi:[1,0]
	v_pk_mul_f32 v[18:19], v[18:19], v[0:1] op_sel_hi:[1,0]
	v_pk_mul_f32 v[16:17], v[16:17], v[0:1] op_sel_hi:[1,0]
	v_add_f32_e32 v219, v94, v88
	v_cvt_pk_bf16_f32 v88, v224, v226
	v_cvt_pk_bf16_f32 v89, v234, v236
	v_cvt_pk_bf16_f32 v90, v81, v80
	v_cvt_pk_bf16_f32 v91, v85, v84
	v_cvt_pk_bf16_f32 v92, v101, v100
	v_cvt_pk_bf16_f32 v93, v103, v102
	v_cvt_pk_bf16_f32 v94, v107, v106
	v_cvt_pk_bf16_f32 v95, v109, v108
	v_cvt_pk_bf16_f32 v96, v225, v227
	v_cvt_pk_bf16_f32 v97, v235, v237
	v_cvt_pk_bf16_f32 v98, v15, v14
	v_cvt_pk_bf16_f32 v99, v83, v82
	v_cvt_pk_bf16_f32 v80, v87, v86
	v_cvt_pk_bf16_f32 v81, v105, v104
	v_cvt_pk_bf16_f32 v82, v231, v230
	v_cvt_pk_bf16_f32 v83, v233, v232
	s_nop 0
	v_mfma_f32_32x32x16_bf16 v[64:79], v[184:187], v[88:91], v[64:79]
	v_mfma_f32_32x32x16_bf16 v[64:79], v[196:199], v[92:95], v[64:79]
	v_mfma_f32_32x32x16_bf16 v[64:79], v[192:195], v[96:99], v[64:79]
	v_mfma_f32_32x32x16_bf16 v[64:79], v[188:191], v[80:83], v[64:79]
	ds_read_b64_tr_b16 v[84:85], v222 offset:51328
	ds_read_b64_tr_b16 v[86:87], v222 offset:53888
	ds_read_b64_tr_b16 v[100:101], v222 offset:56448
	ds_read_b64_tr_b16 v[102:103], v222 offset:59008
	ds_read_b64_tr_b16 v[104:105], v222 offset:61568
	ds_read_b64_tr_b16 v[106:107], v222 offset:64128
	ds_read_b64_tr_b16 v[108:109], v218 offset:15488
	ds_read_b64_tr_b16 v[110:111], v218 offset:18048
	v_mfma_f32_32x32x16_bf16 v[48:63], v[180:183], v[88:91], v[48:63]
	v_mfma_f32_32x32x16_bf16 v[48:63], v[10:13], v[92:95], v[48:63]
	v_mfma_f32_32x32x16_bf16 v[48:63], v[6:9], v[96:99], v[48:63]
	v_mfma_f32_32x32x16_bf16 v[48:63], v[2:5], v[80:83], v[48:63]
	ds_read_b64_tr_b16 v[2:3], v222 offset:51392
	ds_read_b64_tr_b16 v[4:5], v222 offset:53952
	ds_read_b64_tr_b16 v[6:7], v222 offset:56512
	ds_read_b64_tr_b16 v[8:9], v222 offset:59072
	ds_read_b64_tr_b16 v[10:11], v222 offset:61632
	ds_read_b64_tr_b16 v[12:13], v222 offset:64192
	ds_read_b64_tr_b16 v[180:181], v218 offset:15552
	ds_read_b64_tr_b16 v[182:183], v218 offset:18112
	s_waitcnt lgkmcnt(14)
; #define MFMA32(a, b, c) __builtin_amdgcn_mfma_f32_32x32x16_bf16((a), (b), (c), 0, 0, 0)
; __device__ __forceinline__ bf16x8 cat44(s16x4 lo, s16x4 hi) { return (bf16x8){lo[0], lo[1], lo[2], lo[3], hi[0], hi[1], hi[2], hi[3]}; }
; #define ATT_LDV(buf, d) do { _Pragma("unroll") for (int kb = 0; kb < 2; ++kb) _Pragma("unroll") for (int s = 0; s < 2; ++s) { \
;                 const LAS unsigned char* p_ = Vb + vlane + (32 * kb + 16 * s) * VSTR + (d) * 64; vl[buf][2 * kb + s] = trread(p_); vh[buf][2 * kb + s] = trread(p_ + 8 * VSTR); } } while (0)
; template <int NKS, bool ALLIN = false> ...
;     ...
;             lrun = lrun * alpha + ls;
;     ...
;             for (int d = 0; d < 4; ++d) {
; #pragma unroll
;                 for (int j = 0; j < 4; ++j) o[d] = MFMA32(cat44(vl[d & 1][j], vh[d & 1][j]), pf[j], o[d]);
;                 __builtin_amdgcn_sched_barrier(0);
;                 if (d + 2 < 4) { ATT_LDV(d & 1, d + 2); __builtin_amdgcn_sched_barrier(0); }
;             }
	v_mfma_f32_32x32x16_bf16 v[32:47], v[84:87], v[88:91], v[32:47]
	s_waitcnt lgkmcnt(12)
	v_mfma_f32_32x32x16_bf16 v[32:47], v[100:103], v[92:95], v[32:47]
	s_waitcnt lgkmcnt(10)
	v_mfma_f32_32x32x16_bf16 v[32:47], v[104:107], v[96:99], v[32:47]
	s_waitcnt lgkmcnt(8)
	v_mfma_f32_32x32x16_bf16 v[32:47], v[108:111], v[80:83], v[32:47]
	s_waitcnt lgkmcnt(6)
	v_mfma_f32_32x32x16_bf16 v[16:31], v[2:5], v[88:91], v[16:31]
	s_waitcnt lgkmcnt(4)
	v_mfma_f32_32x32x16_bf16 v[16:31], v[6:9], v[92:95], v[16:31]
	s_waitcnt lgkmcnt(2)
	v_mfma_f32_32x32x16_bf16 v[16:31], v[10:13], v[96:99], v[16:31]
	s_waitcnt lgkmcnt(0)
	v_mfma_f32_32x32x16_bf16 v[16:31], v[180:183], v[80:83], v[16:31]
	v_fmac_f32_e32 v219, v214, v0
	v_mov_b32_e32 v214, v219
	v_mov_b32_e32 v219, v223
	s_andn2_b64 vcc, exec, s[16:17]
	s_cbranch_vccz .LBB0_104
	s_branch .LBB0_105
	s_nop 0
	s_nop 0
	s_nop 0
	s_nop 0
	s_nop 0

; #define LAS __attribute__((address_space(3)))
; #define MK_TID() ({ int w_ = wid0, z_ = 0; asm volatile("" : "+s"(w_), "+s"(z_)); w_ * 64 + (int)__builtin_amdgcn_mbcnt_hi(~0u, __builtin_amdgcn_mbcnt_lo(~0u, (unsigned)z_)); })
; __global__ void __launch_bounds__(512, 2) mk_fwd(Args a_) {
;     ...
;             const int tid = MK_TID(), lane = tid & 63, wid = __builtin_amdgcn_readfirstlane(tid >> 6), gw = bid * 8 + wid, NGW = G * 8;
;             LAS float* scr = (LAS float*)(lds + wid * 16384);
; #pragma nounroll
;             for (int it = gw; it < 5632; it += NGW) tr_mat_item(a, 11, it, scr, lane);
.LBB0_736:
	s_mov_b32 s4, s39
	s_mov_b32 s5, s58
	s_nop 0
	v_mbcnt_lo_u32_b32 v0, -1, s4
	v_mbcnt_hi_u32_b32 v0, -1, v0
	v_lshl_add_u32 v2, s5, 6, v0
	s_nop 0
	v_readfirstlane_b32 s4, v2
	s_ashr_i32 s5, s4, 6
	s_lshl_b32 s4, s34, 3
	s_add_i32 s4, s5, s4
	s_cmpk_lt_i32 s56, 0xc8
	s_cbranch_scc1 .Lwd_even
	s_sub_i32 s4, s34, 0x90
	s_cmp_lt_i32 s4, 0
	s_cbranch_scc1 .LBB0_739
	s_lshl_b32 s4, s4, 3
	s_add_i32 s4, s5, s4
	s_sub_i32 s60, s56, 0x90
	s_lshl_b32 s60, s60, 3
.Lwd_even:
	s_cmpk_gt_i32 s4, 0x15ff
	s_cbranch_scc1 .LBB0_739
	s_load_dwordx2 s[6:7], s[0:1], 0xf8
	s_lshl_b32 s5, s5, 14
	v_and_b32_e32 v2, 7, v0
	s_add_i32 s5, s5, 0
	v_bfe_u32 v24, v0, 3, 3
	v_lshlrev_b32_e32 v0, 4, v2
	s_waitcnt vmcnt(4) lgkmcnt(0)
	v_lshl_add_u64 v[18:19], s[6:7], 0, v[0:1]
	v_add_u32_e32 v4, s5, v0
	v_mul_u32_u24_e32 v6, 0x420, v2
	v_lshl_add_u64 v[2:3], s[66:67], 0, v[0:1]
	v_lshlrev_b32_e32 v0, 2, v24
	s_mov_b64 s[6:7], 0x3400000
	v_add3_u32 v0, s5, v6, v0
	s_mul_i32 s5, s4, 0x2c000
	v_mul_u32_u24_e32 v5, 0x84, v24
	v_lshl_add_u64 v[20:21], v[2:3], 0, s[6:7]
	v_mov_b32_e32 v2, s5
	s_movk_i32 s5, 0x1600
	v_mad_u32_u24 v25, v24, s5, v2
	s_lshl_b32 s5, s4, 5
	s_lshl_b32 s6, s60, 5
	v_add_u32_e32 v26, v4, v5

; #define LAS __attribute__((address_space(3)))
; #define MK_TID() ({ int w_ = wid0, z_ = 0; asm volatile("" : "+s"(w_), "+s"(z_)); w_ * 64 + (int)__builtin_amdgcn_mbcnt_hi(~0u, __builtin_amdgcn_mbcnt_lo(~0u, (unsigned)z_)); })
; __global__ void __launch_bounds__(512, 2) mk_fwd(Args a_) {
;     ...
;             for (int it = gw; it < 5632; it += NGW) tr_mat_item(a, 11, it, scr, lane);
;         } else if (ph == 5) {
;             const int tid = MK_TID(), lane = tid & 63, wid = __builtin_amdgcn_readfirstlane(tid >> 6);
;             LAS float* scr = (LAS float*)(lds + wid * 16384);
;             if (G > 2 * NML) { if (bid >= NML) {
; #pragma nounroll
;                 for (int it = (bid - NML) * 8 + wid; it < 11264; it += (G - NML) * 8) tr_mat_item(a, 10, it, scr, lane); } }
;             else {
; #pragma nounroll
;                 for (int it = bid * 8 + wid; it < 11264; it += G * 8) tr_mat_item(a, 10, it, scr, lane); }
;         }
;         if (ph + 1 < ph_hi) { if (ph >= 1000) grid.sync(); else xcd_barrier(xbar); }
.LBB0_739:
	v_readlane_b32 s60, v253, 53
	s_mov_b64 s[12:13], 0
	s_andn2_b64 vcc, exec, s[14:15]
	s_mov_b64 s[20:21], 0
	s_cbranch_vccnz .LBB0_741
	s_cmp_eq_u32 s91, 5
	s_cselect_b64 s[20:21], -1, 0
